# mixer A: next unit Q rows prefetched into spare VGPRs behind the current unit drain (with the K/V prefetch), consumed by v_mov at the next unit start
# baseline (speedup 1.0000x reference)
; #define DEC_E(u_, sb_, S_, h_, qb_) do { if ((u_) < 2048) { const int s_ = (u_) >> 8, rem_ = (u_) & 255; h_ = rem_ >> 5; qb_ = rem_ & 31; S_ = 8192; sb_ = s_ * 8192; } \
;                 else { const int u2_ = (u_) - 2048; const int s_ = u2_ >> 7, rem_ = u2_ & 127; h_ = rem_ >> 4; qb_ = rem_ & 15; S_ = 4096; sb_ = MP + s_ * 4096; } } while (0)
; template<int THRL,bool WIN,int DM,int ODM,int DV,int QMODE> __device__ __forceinline__ void attn_unit(const bf16*Qp,const bf16*__restrict__ Kp,const bf16*__restrict__ Vp,bf16*Op,const int q0,const int t_lo,const int NT,const float sink2,char*shm,const float*qgain,const float*qtab,const int b0,const ...
;     ...
;   bf16x8 qr[4];
;   #pragma unroll
;   for(int d0=0;d0<4;++d0)qr[d0]=*reinterpret_cast<const bf16x8*>(&Qw[(long)r32*DM+d0*16+hi*8]);
; __global__ void __launch_bounds__(NWAVES * 64, 2) encoder_fwd(Args args) {
;     ...
;             { int b0 = 0; bool pre = false;
;             for (int u = vcu; u < 2048 + 512; u += G) {
;                 int sb, S, vh, qb; DEC_E(u, sb, S, vh, qb);
;                 const int q0 = qb * 256;
;                 const attn_body::bf16 *nK = nullptr, *nV = nullptr;
;                 if (u + G < 2048 + 512) { int sbn, Sn, vhn, qbn; DEC_E(u + G, sbn, Sn, vhn, qbn); nK = (const attn_body::bf16*)(QKV + (size_t)sbn * EVEN_IN + 512 + 64 * (vhn >> 2)); nV = (const attn_body::bf16*)(QKV + (size_t)sbn * EVEN_IN + 640 + 64 * (vhn >> 2)); }
;                 attn_body::attn_unit<8, false, EVEN_IN, 1024, 64, 1>((const attn_body::bf16*)(QKV + (size_t)(sb + q0) * EVEN_IN + 64 * vh), (const attn_body::bf16*)(QKV + (size_t)sb * EVEN_IN + 512 + 64 * (vh >> 2)),
;                     (const attn_body::bf16*)(QKV + (size_t)sb * EVEN_IN + 640 + 64 * (vh >> 2)), (attn_body::bf16*)(ATT + (size_t)(sb + q0) * 1024 + 64 * vh), q0, 0, S / 64, 0.f, (char*)lds, qgainA, (const float*)axT, b0, pre, nK, nV);
.LBB0_380:
	s_and_b32 s15, s15, 7
	s_and_b64 s[24:25], s[6:7], exec
	s_cselect_b32 s17, 31, 15
	s_and_b32 s13, s13, s17
	s_lshl_b32 s13, s13, 8
	s_add_i32 s82, s14, s13
	s_ashr_i32 s83, s82, 31
	s_mul_i32 s17, s82, 0x1200
	s_mul_hi_i32 s14, s82, 0x1200
	s_add_u32 s21, s28, s17
	s_addc_u32 s14, s29, s14
	s_lshl_b32 s17, s15, 6
	s_lshl_b32 s15, s15, 7
	s_add_u32 s15, s21, s15
	s_addc_u32 s21, s14, 0
	v_and_b32_e32 v205, 31, v74
	v_lshrrev_b32_e32 v206, 5, v203
	s_lshl_b32 s80, s16, 5
	s_ashr_i32 s81, s80, 31
	s_mul_i32 s14, s16, 0x24000
	v_mul_u32_u24_e32 v1, 0x900, v205
	v_lshlrev_b32_e32 v18, 3, v206
	s_mul_hi_i32 s24, s80, 0x1200
	s_add_u32 s14, s15, s14
	v_or_b32_e32 v1, v18, v1
	s_addc_u32 s15, s21, s24
	v_lshlrev_b32_e32 v1, 1, v1
	s_and_b64 vcc, exec, s[4:5]
	s_cbranch_vccnz .Lmy_qpre
	global_load_dwordx4 v[46:49], v1, s[14:15]
	global_load_dwordx4 v[50:53], v1, s[14:15] offset:32
	global_load_dwordx4 v[62:65], v1, s[14:15] offset:64
	global_load_dwordx4 v[66:69], v1, s[14:15] offset:96
	s_branch .Lmy_qdone
.Lmy_qpre:
	s_waitcnt vmcnt(0)
	v_mov_b64_e32 v[46:47], v[218:219]
	v_mov_b64_e32 v[48:49], v[220:221]
	v_mov_b64_e32 v[50:51], v[222:223]
	v_mov_b64_e32 v[52:53], v[224:225]
	v_mov_b64_e32 v[62:63], v[226:227]
	v_mov_b64_e32 v[64:65], v[228:229]
	v_mov_b64_e32 v[66:67], v[230:231]
	v_mov_b64_e32 v[68:69], v[232:233]
.Lmy_qdone:
	s_add_i32 s14, s3, 0x2000
	v_mov_b32_e32 v2, v0
	v_mov_b32_e32 v3, v0
	v_mov_b32_e32 v4, v0
	v_mov_b32_e32 v5, v0
	v_mov_b32_e32 v6, v0
	v_mov_b32_e32 v7, v0
	v_mov_b32_e32 v8, v0
	v_mov_b32_e32 v9, v0
	v_mov_b32_e32 v10, v0
	v_mov_b32_e32 v11, v0
	v_mov_b32_e32 v12, v0
	v_mov_b32_e32 v13, v0
	v_mov_b32_e32 v14, v0
	v_mov_b32_e32 v15, v0
	s_cmpk_lg_i32 s3, 0x4000
	v_mov_b32_e32 v1, v0
	v_mov_b64_e32 v[16:17], v[14:15]
	s_cselect_b32 s27, s14, 0
	v_mov_b64_e32 v[14:15], v[12:13]
	v_mov_b64_e32 v[12:13], v[10:11]
	v_mov_b64_e32 v[10:11], v[8:9]
	v_mov_b64_e32 v[8:9], v[6:7]
	v_mov_b64_e32 v[6:7], v[4:5]
	v_mov_b64_e32 v[4:5], v[2:3]
	v_mov_b64_e32 v[2:3], v[0:1]
	s_and_b64 vcc, exec, s[4:5]
	s_cbranch_vccnz .LBB0_382
	v_lshl_add_u64 v[20:21], v[196:197], 0, s[42:43]
	s_add_i32 s4, s22, s27
	s_mov_b32 s5, m0
	s_mov_b32 m0, s4
	s_nop 0
	global_load_lds_dwordx4 v[20:21], off
	s_mov_b32 m0, s5

; #define SBAR() __builtin_amdgcn_sched_barrier(0)
;   #define PKW(P,B) cvtpk_s(P[B],P[B+1])
; template<int THRL,bool WIN,int DM,int ODM,int DV,int QMODE> __device__ __forceinline__ void attn_unit(const bf16*Qp,const bf16*__restrict__ Kp,const bf16*__restrict__ Vp,bf16*Op,const int q0,const int t_lo,const int NT,const float sink2,char*shm,const float*qgain,const float*qtab,const int b0,const ...
;     ...
;   { float sacc=pB0[0]+pB0[1]; _Pragma("unroll") for(int r=2;r<16;++r)sacc+=pB0[r]; _Pragma("unroll") for(int r=0;r<16;++r)sacc+=pB1[r]; l_reg+=sacc;
;     pw0=(u32x4){PKW(pB0,0),PKW(pB0,2),PKW(pB0,4),PKW(pB0,6)};pw1=(u32x4){PKW(pB0,8),PKW(pB0,10),PKW(pB0,12),PKW(pB0,14)};pw2=(u32x4){PKW(pB1,0),PKW(pB1,2),PKW(pB1,4),PKW(pB1,6)};pw3=(u32x4){PKW(pB1,8),PKW(pB1,10),PKW(pB1,12),PKW(pB1,14)};
;     SBAR(); pv<DV/32>(o,vb0+VM*sl_cur,PAF(0),PAF(1),PAF(2),PAF(3)); }
;   if(nKp){
;     const int n0=(sl_cur==(NSLOT-1)*SLOTB)?0:sl_cur+SLOTB,n1=(n0==(NSLOT-1)*SLOTB)?0:n0+SLOTB,n2=(n1==(NSLOT-1)*SLOTB)?0:n1+SLOTB;
;     const bf16*nks=nKp+(long)lane*DM+wid*8; const bf16*nvs=nVp+(long)(16*(wid&3)+(lane>>2))*DM+(wid>>2)*32+(lane&3)*8;
;     glds16(nks,(unsigned)__builtin_amdgcn_readfirstlane(kdst+n0));
;     glds16(nvs,(unsigned)__builtin_amdgcn_readfirstlane(vdst+VM*n0)); if constexpr(DV==128){ glds16(nvs+64,(unsigned)__builtin_amdgcn_readfirstlane(vdst+VM*n0+8192)); }
;     glds16(nks+(long)KVBLK*DM,(unsigned)__builtin_amdgcn_readfirstlane(kdst+n1));
;     glds16(nks+(long)2*KVBLK*DM,(unsigned)__builtin_amdgcn_readfirstlane(kdst+n2)); }
; __global__ void __launch_bounds__(NWAVES * 64, 2) encoder_fwd(Args args) {
;     ...
;             { int b0 = 0; bool pre = false;
;             for (int u = vcu; u < 2048 + 512; u += G) {
;                 int sb, S, vh, qb; DEC_E(u, sb, S, vh, qb);
;                 const int q0 = qb * 256;
;                 const attn_body::bf16 *nK = nullptr, *nV = nullptr;
;                 if (u + G < 2048 + 512) { int sbn, Sn, vhn, qbn; DEC_E(u + G, sbn, Sn, vhn, qbn); nK = (const attn_body::bf16*)(QKV + (size_t)sbn * EVEN_IN + 512 + 64 * (vhn >> 2)); nV = (const attn_body::bf16*)(QKV + (size_t)sbn * EVEN_IN + 640 + 64 * (vhn >> 2)); }
;                 attn_body::attn_unit<8, false, EVEN_IN, 1024, 64, 1>((const attn_body::bf16*)(QKV + (size_t)(sb + q0) * EVEN_IN + 64 * vh), (const attn_body::bf16*)(QKV + (size_t)sb * EVEN_IN + 512 + 64 * (vh >> 2)),
.LBB0_447:
	s_cmp_lg_u32 0, -1
	s_cselect_b32 s2, 0, 0
	v_readlane_b32 s15, v255, 35
	s_addk_i32 s2, 0x6000
	v_add3_u32 v51, v195, s2, v191
	v_cvt_pk_bf16_f32 v52, v82, v83
	v_cvt_pk_bf16_f32 v53, v84, v85
	v_cvt_pk_bf16_f32 v54, v86, v87
	v_cvt_pk_bf16_f32 v55, v88, v89
	v_cvt_pk_bf16_f32 v56, v90, v91
	v_cvt_pk_bf16_f32 v57, v92, v93
	v_cvt_pk_bf16_f32 v58, v94, v95
	v_cvt_pk_bf16_f32 v59, v96, v97
	v_cvt_pk_bf16_f32 v60, v34, v35
	v_cvt_pk_bf16_f32 v61, v36, v37
	v_cvt_pk_bf16_f32 v62, v38, v39
	v_cvt_pk_bf16_f32 v63, v40, v41
	v_cvt_pk_bf16_f32 v64, v42, v43
	v_cvt_pk_bf16_f32 v65, v44, v45
	v_cvt_pk_bf16_f32 v66, v46, v47
	v_cvt_pk_bf16_f32 v67, v48, v49
	v_add3_u32 v51, v51, v207, s14
	ds_read_b64_tr_b16 v[68:69],v51 offset:0
	ds_read_b64_tr_b16 v[70:71],v51 offset:512
	ds_read_b64_tr_b16 v[72:73],v51 offset:1024
	ds_read_b64_tr_b16 v[74:75],v51 offset:1536
	ds_read_b64_tr_b16 v[76:77],v51 offset:2048
	ds_read_b64_tr_b16 v[78:79],v51 offset:2560
	ds_read_b64_tr_b16 v[98:99],v51 offset:3072
	ds_read_b64_tr_b16 v[100:101],v51 offset:3584
	s_waitcnt lgkmcnt(0)
	s_nop 0
	v_mfma_f32_32x32x16_bf16 v[2:17], v[52:55], v[68:71], v[2:17]
	ds_read_b64_tr_b16 v[68:69],v51 offset:4096
	ds_read_b64_tr_b16 v[70:71],v51 offset:4608
	v_mfma_f32_32x32x16_bf16 v[2:17], v[56:59], v[72:75], v[2:17]
	ds_read_b64_tr_b16 v[72:73],v51 offset:5120
	ds_read_b64_tr_b16 v[74:75],v51 offset:5632
	v_mfma_f32_32x32x16_bf16 v[2:17], v[60:63], v[76:79], v[2:17]
	ds_read_b64_tr_b16 v[76:77],v51 offset:6144
	ds_read_b64_tr_b16 v[78:79],v51 offset:6656
	v_mfma_f32_32x32x16_bf16 v[2:17], v[64:67], v[98:101], v[2:17]
	ds_read_b64_tr_b16 v[98:99],v51 offset:7168
	ds_read_b64_tr_b16 v[100:101],v51 offset:7680
	s_waitcnt lgkmcnt(0)
	v_mfma_f32_32x32x16_bf16 v[18:33], v[52:55], v[68:71], v[18:33]
	s_cmp_eq_u64 s[76:77], 0
	v_mfma_f32_32x32x16_bf16 v[18:33], v[56:59], v[72:75], v[18:33]
	v_mfma_f32_32x32x16_bf16 v[18:33], v[60:63], v[76:79], v[18:33]
	v_mfma_f32_32x32x16_bf16 v[18:33], v[64:67], v[98:101], v[18:33]
	s_cbranch_scc1 .LBB0_449
	s_add_i32 s2, s14, 0x2000
	s_cmpk_lg_i32 s14, 0x4000
	s_cselect_b32 s2, s2, 0
	s_add_i32 s3, s2, 0x2000
	s_cmpk_lg_i32 s2, 0x4000
	s_cselect_b32 s3, s3, 0
	s_add_i32 s6, s3, 0x2000
	v_mov_b32_e32 v191, v0
	v_mov_b32_e32 v193, v0
	s_cmpk_lg_i32 s3, 0x4000
	v_lshl_add_u64 v[52:53], s[76:77], 0, v[190:191]
	v_lshl_add_u64 v[54:55], s[78:79], 0, v[192:193]
	s_cselect_b32 s6, s6, 0
	v_lshl_add_u64 v[52:53], s[84:85], 1, v[52:53]
	v_lshl_add_u64 v[54:55], s[86:87], 1, v[54:55]
	v_mov_b32_e32 v195, v0
	s_add_i32 s7, s2, s22
	s_mov_b32 s13, m0
	s_mov_b32 m0, s7
	s_nop 0
	global_load_lds_dwordx4 v[52:53], off
	s_mov_b32 m0, s13
	v_lshl_add_u64 v[54:55], v[54:55], 0, v[194:195]
	s_add_i32 s2, s2, s23
	s_mov_b32 s7, m0
	s_mov_b32 m0, s2
	s_nop 0
	global_load_lds_dwordx4 v[54:55], off
	s_mov_b32 m0, s7
	v_lshl_add_u64 v[54:55], v[52:53], 0, s[54:55]
	s_add_i32 s2, s3, s22
	s_mov_b32 s3, m0
	s_mov_b32 m0, s2
	s_nop 0
	global_load_lds_dwordx4 v[54:55], off
	s_mov_b32 m0, s3
	v_lshl_add_u64 v[52:53], v[52:53], 0, s[42:43]
	s_add_i32 s2, s6, s22
	s_mov_b32 s3, m0
	s_mov_b32 m0, s2
	s_nop 0
	global_load_lds_dwordx4 v[52:53], off
	s_mov_b32 m0, s3
	s_lshl_b32 s64, s12, 5
	s_cmpk_lt_i32 s12, 0x800
	s_movk_i32 s65, 0xe000
	s_cselect_b32 s65, s65, 0x7ffff000
	s_cselect_b32 s68, 5, 4
	s_cselect_b32 s69, 31, 15
	s_and_b32 s64, s64, s65
	s_lshr_b32 s68, s12, s68
	s_and_b32 s68, s68, 7
	s_and_b32 s69, s12, s69
	s_lshl_b32 s69, s69, 8
	s_add_i32 s64, s64, s69
	s_add_i32 s64, s64, s80
	s_mul_i32 s66, s64, 0x1200
	s_mul_hi_u32 s67, s64, 0x1200
	s_lshl_b32 s68, s68, 7
	s_add_u32 s66, s66, s28
	s_addc_u32 s67, s67, s29
	s_add_u32 s66, s66, s68
	s_addc_u32 s67, s67, 0
	v_mul_u32_u24_e32 v233, 0x900, v205
	v_lshl_or_b32 v233, v206, 3, v233
	v_lshlrev_b32_e32 v233, 1, v233
	global_load_dwordx4 v[218:221], v233, s[66:67]
	global_load_dwordx4 v[222:225], v233, s[66:67] offset:32
	global_load_dwordx4 v[226:229], v233, s[66:67] offset:64
	global_load_dwordx4 v[230:233], v233, s[66:67] offset:96
